# nt on the read-once input loads of phase 0 (f32 weights for the transposes, x for the first row-norm), on top of nt row-norm loads
# speedup vs baseline: 1.0133x; 1.0133x over previous
; DI void phase_prep(const Ctx& c, char* smem) {
;     ...
;     const float* src = nullptr; bf16_t* dst = nullptr; int K = 64, Ns = 0, Np = 64, r = u;
;     for (int mi = 0; mi < 13; ++mi) { get_tdesc(c, mi, src, dst, K, Ns, Np); const int nt = (K / 64) * (Np / 64); if (r < nt) break; r -= nt; }
;     const int nkb = K / 64, kb = r % nkb, nb = r / nkb;
;     f32x4 ld_[4];
; #pragma unroll
;     for (int i = 0; i < 4; ++i) { const int k = i * 16 + (tid >> 4), gn = nb * 64 + (tid & 15) * 4; ld_[i] = gn < Ns ? *(const f32x4*)(src + (size_t)(kb * 64 + k) * Ns + gn) : (f32x4){0.f, 0.f, 0.f, 0.f}; }
.LBB0_37:
	v_cvt_f32_ubyte0_e32 v2, s40
	v_rcp_iflag_f32_e32 v2, v2
	s_sub_i32 s42, 0, s40
	s_abs_i32 s41, s38
	s_ashr_i32 s31, s38, 31
	v_mul_f32_e32 v2, 0x4f7ffffe, v2
	v_cvt_u32_f32_e32 v2, v2
	v_mov_b32_e32 v6, 0
	v_mov_b32_e32 v7, 0
	v_mov_b32_e32 v8, 0
	v_readfirstlane_b32 s43, v2
	s_mul_i32 s42, s42, s43
	s_mul_hi_u32 s42, s43, s42
	s_add_i32 s43, s43, s42
	s_mul_hi_u32 s42, s41, s43
	s_mul_i32 s43, s42, s40
	s_sub_i32 s41, s41, s43
	s_add_i32 s44, s42, 1
	s_sub_i32 s43, s41, s40
	s_cmp_ge_u32 s41, s40
	s_cselect_b32 s42, s44, s42
	s_cselect_b32 s41, s43, s41
	s_add_i32 s43, s42, 1
	s_cmp_ge_u32 s41, s40
	s_cselect_b32 s41, s43, s42
	s_xor_b32 s41, s41, s31
	s_sub_i32 s31, s41, s31
	s_mul_i32 s40, s31, s40
	s_lshl_b32 s31, s31, 6
	s_sub_i32 s38, s38, s40
	v_or_b32_e32 v2, s31, v24
	s_lshl_b32 s38, s38, 6
	v_ashrrev_i32_e32 v3, 31, v2
	v_cmp_gt_i32_e32 vcc, s39, v2
	v_add_u32_e32 v29, s38, v25
	v_lshl_add_u64 v[20:21], v[2:3], 2, s[36:37]
	v_mov_b32_e32 v2, 0
	v_mov_b32_e32 v9, 0
	s_and_saveexec_b64 s[36:37], vcc
	s_cbranch_execz .LBB0_39
	v_mad_i64_i32 v[4:5], s[40:41], v29, s39, 0
	v_lshl_add_u64 v[4:5], v[4:5], 2, v[20:21]
	global_load_dwordx4 v[6:9], v[4:5], off nt
.LBB0_39:
	s_or_b64 exec, exec, s[36:37]
	v_mov_b32_e32 v3, 0
	v_mov_b32_e32 v4, 0
	v_mov_b32_e32 v5, 0
	s_and_saveexec_b64 s[36:37], vcc
	s_cbranch_execz .LBB0_41
	v_add_u32_e32 v2, 16, v29
	v_mad_i64_i32 v[2:3], s[40:41], v2, s39, 0
	v_lshl_add_u64 v[2:3], v[2:3], 2, v[20:21]
	global_load_dwordx4 v[2:5], v[2:3], off nt
.LBB0_41:
	s_or_b64 exec, exec, s[36:37]
	v_mov_b32_e32 v10, 0
	v_mov_b32_e32 v14, 0
	v_mov_b32_e32 v15, 0
	v_mov_b32_e32 v16, 0
	v_mov_b32_e32 v17, 0
	s_and_saveexec_b64 s[36:37], vcc
	s_cbranch_execz .LBB0_43
	v_add_u32_e32 v11, 32, v29
	v_mad_i64_i32 v[12:13], s[40:41], v11, s39, 0
	v_lshl_add_u64 v[12:13], v[12:13], 2, v[20:21]
	global_load_dwordx4 v[14:17], v[12:13], off nt
.LBB0_43:
	s_or_b64 exec, exec, s[36:37]
	v_mov_b32_e32 v11, 0
	v_mov_b32_e32 v12, 0
	v_mov_b32_e32 v13, 0
	s_and_saveexec_b64 s[36:37], vcc
	s_cbranch_execz .LBB0_9
	v_add_u32_e32 v10, 48, v29
	v_mad_i64_i32 v[10:11], s[40:41], v10, s39, 0
	v_lshl_add_u64 v[10:11], v[10:11], 2, v[20:21]
	global_load_dwordx4 v[10:13], v[10:11], off nt
	s_branch .LBB0_9

; DI void phase_rmsnorm(const Ctx& c, const float* src, const float* w) {
;     ...
;   for (int u = blockIdx.x; u < NTOK / 8; u += gridDim.x) {
;     const int row = u * 8 + wid * 2;
;     const float* xr = src + (size_t)row * 1024;
;     f32x4 v[2][4];
; #pragma unroll
;     for (int r = 0; r < 2; ++r)
; #pragma unroll
;       for (int i = 0; i < 4; ++i) v[r][i] = *(const f32x4*)(xr + r * 1024 + i * 256 + lane * 4);
; #pragma unroll
;     for (int r = 0; r < 2; ++r) {
;       float ss = 0.f;
; #pragma unroll
;       for (int i = 0; i < 4; ++i) ss += v[r][i][0] * v[r][i][0] + v[r][i][1] * v[r][i][1] + v[r][i][2] * v[r][i][2] + v[r][i][3] * v[r][i][3];
;       ss = wave_sum(ss);
.LBB0_47:
	v_ashrrev_i32_e32 v39, 31, v38
	v_lshlrev_b64 v[18:19], 12, v[38:39]
	v_lshl_add_u64 v[18:19], v[34:35], 0, v[18:19]
	global_load_dwordx4 v[44:47], v[18:19], off nt
	global_load_dwordx4 v[48:51], v[18:19], off offset:1024 nt
	global_load_dwordx4 v[52:55], v[18:19], off offset:2048 nt
	global_load_dwordx4 v[56:59], v[18:19], off offset:3072 nt
	v_add_co_u32_e32 v18, vcc, 0x1000, v18
	s_add_i32 s4, s4, s1
	s_nop 0
	v_addc_co_u32_e32 v19, vcc, 0, v19, vcc
	global_load_dwordx4 v[30:33], v[18:19], off nt
	global_load_dwordx4 v[26:29], v[18:19], off offset:1024 nt
	global_load_dwordx4 v[22:25], v[18:19], off offset:2048 nt
	s_nop 0
	global_load_dwordx4 v[18:21], v[18:19], off offset:3072 nt
	s_cmpk_gt_i32 s4, 0xfff
	s_waitcnt vmcnt(7)
	v_mov_b32_e32 v62, v45
	s_waitcnt vmcnt(6)
	v_mov_b32_e32 v63, v49
	s_waitcnt vmcnt(5)
	v_mov_b32_e32 v70, v53
	s_waitcnt vmcnt(4)
	v_mov_b32_e32 v71, v57
	v_mov_b32_e32 v60, v44
	v_mov_b32_e32 v61, v48
	v_mov_b32_e32 v68, v52
	v_mov_b32_e32 v69, v56
	v_pk_mul_f32 v[62:63], v[62:63], v[62:63]
	v_pk_mul_f32 v[70:71], v[70:71], v[70:71]
	v_mov_b32_e32 v64, v46
	v_mov_b32_e32 v65, v50
	v_pk_fma_f32 v[60:61], v[60:61], v[60:61], v[62:63]
	v_pk_fma_f32 v[62:63], v[68:69], v[68:69], v[70:71]
	s_waitcnt vmcnt(3)
	v_mov_b32_e32 v70, v31
	s_waitcnt vmcnt(2)
	v_mov_b32_e32 v71, v27
	v_mov_b32_e32 v68, v30
	v_mov_b32_e32 v69, v26
	s_waitcnt vmcnt(1)
	v_mov_b32_e32 v78, v23
	s_waitcnt vmcnt(0)
	v_mov_b32_e32 v79, v19
	v_pk_fma_f32 v[60:61], v[64:65], v[64:65], v[60:61]
	v_pk_mul_f32 v[64:65], v[70:71], v[70:71]
	v_mov_b32_e32 v66, v47
	v_mov_b32_e32 v67, v51
	v_mov_b32_e32 v76, v22
	v_mov_b32_e32 v77, v18
	v_mov_b32_e32 v80, v32
	v_mov_b32_e32 v81, v28
	v_pk_mul_f32 v[70:71], v[78:79], v[78:79]
	v_pk_fma_f32 v[64:65], v[68:69], v[68:69], v[64:65]
	v_mov_b32_e32 v72, v54
	v_mov_b32_e32 v73, v58
	v_mov_b32_e32 v82, v24
	v_mov_b32_e32 v83, v20
	v_mov_b32_e32 v84, v33
	v_mov_b32_e32 v85, v29
	v_pk_fma_f32 v[60:61], v[66:67], v[66:67], v[60:61]
	v_pk_fma_f32 v[66:67], v[76:77], v[76:77], v[70:71]
	v_pk_fma_f32 v[64:65], v[80:81], v[80:81], v[64:65]
	v_mov_b32_e32 v74, v55
	v_mov_b32_e32 v75, v59
	v_mov_b32_e32 v86, v25
	v_mov_b32_e32 v87, v21
	v_pk_fma_f32 v[62:63], v[72:73], v[72:73], v[62:63]
	v_pk_fma_f32 v[66:67], v[82:83], v[82:83], v[66:67]
	v_pk_fma_f32 v[64:65], v[84:85], v[84:85], v[64:65]
	v_pk_fma_f32 v[62:63], v[74:75], v[74:75], v[62:63]
	v_mov_b32_e32 v69, v60
	v_pk_fma_f32 v[66:67], v[86:87], v[86:87], v[66:67]
	v_mov_b32_e32 v68, v64
	v_mov_b32_e32 v60, v65
	v_mov_b32_e32 v71, v62
	v_mov_b32_e32 v70, v66
	v_pk_add_f32 v[60:61], v[68:69], v[60:61]
	v_mov_b32_e32 v62, v67
	v_pk_add_f32 v[60:61], v[60:61], v[70:71]
	s_nop 0
	v_pk_add_f32 v[60:61], v[60:61], v[62:63]
	s_nop 1
	v_mov_b32_dpp v63, v61 quad_perm:[1,0,3,2] row_mask:0xf bank_mask:0xf bound_ctrl:1
	v_mov_b32_dpp v62, v60 quad_perm:[1,0,3,2] row_mask:0xf bank_mask:0xf bound_ctrl:1
	v_pk_add_f32 v[60:61], v[60:61], v[62:63]
	s_nop 1
	v_mov_b32_dpp v63, v61 quad_perm:[2,3,0,1] row_mask:0xf bank_mask:0xf bound_ctrl:1
	v_mov_b32_dpp v62, v60 quad_perm:[2,3,0,1] row_mask:0xf bank_mask:0xf bound_ctrl:1
	v_pk_add_f32 v[60:61], v[60:61], v[62:63]
	s_nop 1
	v_mov_b32_dpp v63, v61 row_half_mirror row_mask:0xf bank_mask:0xf bound_ctrl:1
	v_mov_b32_dpp v62, v60 row_half_mirror row_mask:0xf bank_mask:0xf bound_ctrl:1
	v_pk_add_f32 v[60:61], v[60:61], v[62:63]
	s_nop 1
	v_mov_b32_dpp v63, v61 row_mirror row_mask:0xf bank_mask:0xf bound_ctrl:1
	v_mov_b32_dpp v62, v60 row_mirror row_mask:0xf bank_mask:0xf bound_ctrl:1
	v_pk_add_f32 v[60:61], v[60:61], v[62:63]
	ds_bpermute_b32 v63, v41, v61
	ds_bpermute_b32 v62, v41, v60
	s_waitcnt lgkmcnt(0)
; DI unsigned pack2(float lo, float hi) { const f32x2c v = {lo, hi}; return __builtin_bit_cast(unsigned, __builtin_convertvector(v, bf16x2c)); }
; DI void phase_rmsnorm(const Ctx& c, const float* src, const float* w) {
;     ...
;       ss = wave_sum(ss);
;       const float rs = rsqrtf(ss * (1.0f / 1024.0f) + 1e-5f);
;       bf16_t* o = xn + (size_t)(row + r) * 1024;
; #pragma unroll
;       for (int i = 0; i < 4; ++i) { u32x2 q; q.x = pack2(v[r][i][0] * rs * g[i][0], v[r][i][1] * rs * g[i][1]); q.y = pack2(v[r][i][2] * rs * g[i][2], v[r][i][3] * rs * g[i][3]); *(u32x2*)(o + i * 256 + lane * 4) = q; }
	v_pk_add_f32 v[60:61], v[60:61], v[62:63]
	ds_bpermute_b32 v63, v42, v61
	ds_bpermute_b32 v62, v42, v60
	s_waitcnt lgkmcnt(0)
	v_pk_add_f32 v[60:61], v[60:61], v[62:63]
	s_nop 0
	v_pk_fma_f32 v[60:61], v[60:61], s[0:1], v[40:41] op_sel_hi:[1,0,0]
	v_lshlrev_b64 v[62:63], 11, v[38:39]
	v_mul_f32_e32 v43, 0x4b800000, v61
	v_cmp_gt_f32_e32 vcc, s3, v61
	v_mul_f32_e32 v39, 0x4b800000, v60
	v_lshl_add_u64 v[62:63], v[36:37], 0, v[62:63]
	v_cndmask_b32_e32 v43, v61, v43, vcc
	v_rsq_f32_e32 v43, v43
	s_nop 0
	v_mul_f32_e32 v61, 0x45800000, v43
	v_cndmask_b32_e32 v64, v43, v61, vcc
	v_cmp_gt_f32_e32 vcc, s3, v60
	v_pk_mul_f32 v[44:45], v[44:45], v[64:65] op_sel_hi:[1,0]
	v_pk_mul_f32 v[46:47], v[46:47], v[64:65] op_sel_hi:[1,0]
	v_cndmask_b32_e32 v39, v60, v39, vcc
	v_rsq_f32_e32 v39, v39
	v_pk_mul_f32 v[48:49], v[48:49], v[64:65] op_sel_hi:[1,0]
	v_pk_mul_f32 v[50:51], v[50:51], v[64:65] op_sel_hi:[1,0]
	v_pk_mul_f32 v[52:53], v[52:53], v[64:65] op_sel_hi:[1,0]
	v_pk_mul_f32 v[54:55], v[54:55], v[64:65] op_sel_hi:[1,0]
	v_pk_mul_f32 v[44:45], v[14:15], v[44:45]
	v_pk_mul_f32 v[46:47], v[16:17], v[46:47]
	v_pk_mul_f32 v[58:59], v[58:59], v[64:65] op_sel_hi:[1,0]
	v_pk_mul_f32 v[48:49], v[10:11], v[48:49]
	v_pk_mul_f32 v[50:51], v[12:13], v[50:51]
	v_pk_mul_f32 v[52:53], v[6:7], v[52:53]
	v_pk_mul_f32 v[54:55], v[8:9], v[54:55]
	v_cvt_pk_bf16_f32 v44, v44, v45
	v_cvt_pk_bf16_f32 v45, v46, v47
	v_cvt_pk_bf16_f32 v46, v48, v49
	v_cvt_pk_bf16_f32 v47, v50, v51
	v_cvt_pk_bf16_f32 v48, v52, v53
	v_cvt_pk_bf16_f32 v49, v54, v55
	global_store_dwordx2 v[62:63], v[44:45], off
	global_store_dwordx2 v[62:63], v[46:47], off offset:512
	global_store_dwordx2 v[62:63], v[48:49], off offset:1024
	v_pk_mul_f32 v[44:45], v[4:5], v[58:59]
	v_mul_f32_e32 v43, 0x45800000, v39
	v_cvt_pk_bf16_f32 v51, v44, v45
	v_cndmask_b32_e32 v44, v39, v43, vcc
	v_add_u32_e32 v46, 1, v38
	v_pk_mul_f32 v[56:57], v[56:57], v[64:65] op_sel_hi:[1,0]
	v_ashrrev_i32_e32 v47, 31, v46
	v_pk_mul_f32 v[30:31], v[30:31], v[44:45] op_sel_hi:[1,0]
	v_pk_mul_f32 v[32:33], v[32:33], v[44:45] op_sel_hi:[1,0]
	v_pk_mul_f32 v[26:27], v[26:27], v[44:45] op_sel_hi:[1,0]
	v_pk_mul_f32 v[28:29], v[28:29], v[44:45] op_sel_hi:[1,0]
	v_pk_mul_f32 v[22:23], v[22:23], v[44:45] op_sel_hi:[1,0]
	v_pk_mul_f32 v[24:25], v[24:25], v[44:45] op_sel_hi:[1,0]
	v_pk_mul_f32 v[18:19], v[18:19], v[44:45] op_sel_hi:[1,0]
	v_pk_mul_f32 v[20:21], v[20:21], v[44:45] op_sel_hi:[1,0]
	v_pk_mul_f32 v[56:57], v[2:3], v[56:57]
	v_lshlrev_b64 v[46:47], 11, v[46:47]
	v_pk_mul_f32 v[30:31], v[14:15], v[30:31]
	v_pk_mul_f32 v[32:33], v[16:17], v[32:33]
	v_pk_mul_f32 v[26:27], v[10:11], v[26:27]
	v_pk_mul_f32 v[28:29], v[12:13], v[28:29]
	v_pk_mul_f32 v[22:23], v[6:7], v[22:23]
	v_pk_mul_f32 v[24:25], v[8:9], v[24:25]
	v_pk_mul_f32 v[18:19], v[2:3], v[18:19]
	v_pk_mul_f32 v[20:21], v[4:5], v[20:21]
	v_cvt_pk_bf16_f32 v50, v56, v57
	v_lshl_add_u64 v[46:47], v[36:37], 0, v[46:47]
	v_cvt_pk_bf16_f32 v30, v30, v31
	v_cvt_pk_bf16_f32 v31, v32, v33
	v_cvt_pk_bf16_f32 v26, v26, v27
	v_cvt_pk_bf16_f32 v27, v28, v29
	v_cvt_pk_bf16_f32 v22, v22, v23
	v_cvt_pk_bf16_f32 v23, v24, v25
	v_cvt_pk_bf16_f32 v18, v18, v19
	v_cvt_pk_bf16_f32 v19, v20, v21
	v_add_u32_e32 v38, s2, v38
	global_store_dwordx2 v[62:63], v[50:51], off offset:1536
	global_store_dwordx2 v[46:47], v[30:31], off
	global_store_dwordx2 v[46:47], v[26:27], off offset:512
	global_store_dwordx2 v[46:47], v[22:23], off offset:1024
	global_store_dwordx2 v[46:47], v[18:19], off offset:1536
	s_cbranch_scc0 .LBB0_47
